# P1 epilogue projection stores made write-through (sc1): less dirty L2 to flush at the grid barrier
# speedup vs baseline: 1.0176x; 1.0035x over previous
; __device__ __forceinline__ unsigned cvt_pk_bf16(float lo, float hi) { unsigned r; asm volatile("v_cvt_pk_bf16_f32 %0, %1, %2" : "=v"(r) : "v"(lo), "v"(hi)); return r; }
;     __device__ __forceinline__ void operator()(const f32x4 (&acc)[2][2][4][2], const Unit& u, int wr, int wc, int fr, int fq) const {
;         const int row0 = u.pm * BM + wr * 64 + fr, col0 = u.pn * BM + wc * 32 + 8 * fq, pn = u.pn;
;         const float sc = (pn < 6 || (pn >= 20 && pn < 22) || (pn >= 25 && pn < 27)) ? 0.125f * 1.4426950408889634f : 1.0f;
;         float rsv[2][4];
; #pragma unroll
;         for (int ai = 0; ai < 2; ++ai)
; #pragma unroll
;             for (int m = 0; m < 4; ++m) rsv[ai][m] = rowss[row0 + ai * HALF + m * 16];
; #pragma unroll
;         for (int ai = 0; ai < 2; ++ai)
; #pragma unroll
;             for (int m = 0; m < 4; ++m) { const int row = row0 + ai * HALF + m * 16; const float rs = rsqrtf(rsv[ai][m] * (1.0f / 1024.0f) + 1e-6f) * sc;
; #pragma unroll
;                 for (int bj = 0; bj < 2; ++bj) { const f32x4 v0 = acc[ai][bj][m][0] * rs, v1 = acc[ai][bj][m][1] * rs;
;                     u32x4 w; w.x = cvt_pk_bf16(v0[0], v0[1]); w.y = cvt_pk_bf16(v0[2], v0[3]); w.z = cvt_pk_bf16(v1[0], v1[1]); w.w = cvt_pk_bf16(v1[2], v1[3]);
;                     *(u32x4*)(O + PB(col0 + bj * HALF) + (size_t)row * 64) = w; } }
.LBB0_138:
	v_lshl_add_u32 v140, s57, 8, v154
	v_ashrrev_i32_e32 v141, 31, v140
	s_cmp_lt_i32 s46, 6
	s_cselect_b64 s[12:13], -1, 0
	s_and_b32 s21, s46, 0x7ffffffe
	s_cmp_eq_u32 s21, 20
	s_cselect_b64 s[28:29], -1, 0
	s_or_b64 s[12:13], s[12:13], s[28:29]
	s_sub_i32 s21, s46, 25
	s_cmp_lt_u32 s21, 2
	s_cselect_b64 s[28:29], -1, 0
	s_or_b64 vcc, s[12:13], s[28:29]
	v_cndmask_b32_e32 v157, 1.0, v237, vcc
	v_lshlrev_b64 v[166:167], 7, v[140:141]
	s_mov_b64 s[12:13], 0x4000
	v_lshl_add_u64 v[146:147], v[166:167], 0, s[12:13]
	s_mov_b64 s[12:13], 0x4800
	v_lshl_add_u64 v[144:145], v[166:167], 0, s[12:13]
	s_mov_b64 s[12:13], 0x5000
	v_lshl_add_u64 v[142:143], v[166:167], 0, s[12:13]
	s_mov_b64 s[12:13], 0x5800
	v_or_b32_e32 v152, 16, v140
	v_or_b32_e32 v150, 32, v140
	v_or_b32_e32 v148, 48, v140
	v_lshl_add_u64 v[140:141], v[166:167], 0, s[12:13]
	s_lshl_b32 s12, s46, 8
	s_or_b32 s12, s12, s49
	s_ashr_i32 s12, s12, 6
	s_ashr_i32 s13, s12, 31
	s_lshl_b64 s[28:29], s[12:13], 21
	s_or_b32 s12, s12, 2
	s_ashr_i32 s13, s12, 31
	s_lshl_b64 s[12:13], s[12:13], 21
	v_ashrrev_i32_e32 v153, 31, v152
	v_ashrrev_i32_e32 v151, 31, v150
	v_ashrrev_i32_e32 v149, 31, v148
	s_waitcnt vmcnt(8)
	v_fmamk_f32 v164, v241, 0x3a800000, v230
	v_cmp_gt_f32_e32 vcc, s37, v164
	v_mul_f32_e32 v165, 0x4b800000, v164
	s_nop 0
	v_cndmask_b32_e32 v164, v164, v165, vcc
	v_rsq_f32_e32 v164, v164
	s_nop 0
	v_mul_f32_e32 v165, 0x45800000, v164
	v_cndmask_b32_e32 v164, v164, v165, vcc
	v_mul_f32_e32 v164, v157, v164
	v_pk_mul_f32 v[124:125], v[124:125], v[164:165] op_sel_hi:[1,0]
	v_pk_mul_f32 v[120:121], v[120:121], v[164:165] op_sel_hi:[1,0]
	v_pk_mul_f32 v[126:127], v[126:127], v[164:165] op_sel_hi:[1,0]
	v_pk_mul_f32 v[168:169], v[122:123], v[164:165] op_sel_hi:[1,0]
	v_cvt_pk_bf16_f32 v122, v124, v125
	v_cvt_pk_bf16_f32 v123, v126, v127
	v_cvt_pk_bf16_f32 v124, v120, v121
	v_lshl_add_u64 v[120:121], v[134:135], 0, s[28:29]
	v_lshl_add_u64 v[126:127], v[120:121], 0, v[166:167]
	v_pk_mul_f32 v[116:117], v[116:117], v[164:165] op_sel_hi:[1,0]
	v_pk_mul_f32 v[112:113], v[112:113], v[164:165] op_sel_hi:[1,0]
	v_cvt_pk_bf16_f32 v125, v168, v169
	global_store_dwordx4 v[126:127], v[122:125], off sc1
	v_pk_mul_f32 v[118:119], v[118:119], v[164:165] op_sel_hi:[1,0]
	s_nop 0
	v_pk_mul_f32 v[122:123], v[114:115], v[164:165] op_sel_hi:[1,0]
	v_cvt_pk_bf16_f32 v114, v116, v117
	v_cvt_pk_bf16_f32 v115, v118, v119
	v_cvt_pk_bf16_f32 v116, v112, v113
	v_lshl_add_u64 v[112:113], v[134:135], 0, s[12:13]
	v_lshl_add_u64 v[118:119], v[112:113], 0, v[166:167]
	v_cvt_pk_bf16_f32 v117, v122, v123
	global_store_dwordx4 v[118:119], v[114:117], off sc1
	s_mov_b64 s[12:13], -1
	s_nop 0
	v_fmamk_f32 v114, v242, 0x3a800000, v230
	v_cmp_gt_f32_e32 vcc, s37, v114
	v_mul_f32_e32 v115, 0x4b800000, v114
	v_lshlrev_b64 v[116:117], 7, v[152:153]
	v_cndmask_b32_e32 v114, v114, v115, vcc
	v_rsq_f32_e32 v114, v114
	s_nop 0
	v_mul_f32_e32 v115, 0x45800000, v114
	v_cndmask_b32_e32 v114, v114, v115, vcc
	v_mul_f32_e32 v114, v157, v114
	v_pk_mul_f32 v[108:109], v[108:109], v[114:115] op_sel_hi:[1,0]
	v_pk_mul_f32 v[110:111], v[110:111], v[114:115] op_sel_hi:[1,0]
	v_pk_mul_f32 v[118:119], v[106:107], v[114:115] op_sel_hi:[1,0]
	v_pk_mul_f32 v[106:107], v[104:105], v[114:115] op_sel_hi:[1,0]
	v_cvt_pk_bf16_f32 v104, v108, v109
	v_cvt_pk_bf16_f32 v105, v110, v111
	v_lshl_add_u64 v[108:109], v[120:121], 0, v[116:117]
	v_pk_mul_f32 v[100:101], v[100:101], v[114:115] op_sel_hi:[1,0]
	v_cvt_pk_bf16_f32 v106, v106, v107
	v_cvt_pk_bf16_f32 v107, v118, v119
	global_store_dwordx4 v[108:109], v[104:107], off sc1
	v_pk_mul_f32 v[102:103], v[102:103], v[114:115] op_sel_hi:[1,0]
	s_nop 0
	v_pk_mul_f32 v[104:105], v[98:99], v[114:115] op_sel_hi:[1,0]
	v_pk_mul_f32 v[98:99], v[96:97], v[114:115] op_sel_hi:[1,0]
	v_cvt_pk_bf16_f32 v96, v100, v101
	v_lshl_add_u64 v[100:101], v[112:113], 0, v[116:117]
	v_cvt_pk_bf16_f32 v97, v102, v103
	v_cvt_pk_bf16_f32 v98, v98, v99
	v_cvt_pk_bf16_f32 v99, v104, v105
	global_store_dwordx4 v[100:101], v[96:99], off sc1
	s_nop 1
	v_fmamk_f32 v96, v243, 0x3a800000, v230
	v_cmp_gt_f32_e32 vcc, s37, v96
	v_mul_f32_e32 v97, 0x4b800000, v96
	v_lshlrev_b64 v[98:99], 7, v[150:151]
	v_cndmask_b32_e32 v96, v96, v97, vcc
	v_rsq_f32_e32 v96, v96
	s_nop 0
	v_mul_f32_e32 v97, 0x45800000, v96
	v_cndmask_b32_e32 v96, v96, v97, vcc
	v_mul_f32_e32 v96, v157, v96
	v_pk_mul_f32 v[92:93], v[92:93], v[96:97] op_sel_hi:[1,0]
	v_pk_mul_f32 v[94:95], v[94:95], v[96:97] op_sel_hi:[1,0]
	v_pk_mul_f32 v[100:101], v[90:91], v[96:97] op_sel_hi:[1,0]
	v_pk_mul_f32 v[90:91], v[88:89], v[96:97] op_sel_hi:[1,0]
	v_cvt_pk_bf16_f32 v88, v92, v93
	v_cvt_pk_bf16_f32 v89, v94, v95
	v_lshl_add_u64 v[92:93], v[120:121], 0, v[98:99]
	v_pk_mul_f32 v[84:85], v[84:85], v[96:97] op_sel_hi:[1,0]
	v_cvt_pk_bf16_f32 v90, v90, v91
	v_cvt_pk_bf16_f32 v91, v100, v101
	global_store_dwordx4 v[92:93], v[88:91], off sc1
	v_pk_mul_f32 v[86:87], v[86:87], v[96:97] op_sel_hi:[1,0]
	s_nop 0
	v_pk_mul_f32 v[88:89], v[82:83], v[96:97] op_sel_hi:[1,0]
	v_pk_mul_f32 v[82:83], v[80:81], v[96:97] op_sel_hi:[1,0]
	v_cvt_pk_bf16_f32 v80, v84, v85
	v_lshl_add_u64 v[84:85], v[112:113], 0, v[98:99]
	v_cvt_pk_bf16_f32 v81, v86, v87
	v_cvt_pk_bf16_f32 v82, v82, v83
	v_cvt_pk_bf16_f32 v83, v88, v89
	global_store_dwordx4 v[84:85], v[80:83], off sc1
	s_nop 1
	v_fmamk_f32 v80, v244, 0x3a800000, v230
	v_cmp_gt_f32_e32 vcc, s37, v80
	v_mul_f32_e32 v81, 0x4b800000, v80
	v_lshlrev_b64 v[82:83], 7, v[148:149]
	v_cndmask_b32_e32 v80, v80, v81, vcc
	v_rsq_f32_e32 v80, v80
	s_nop 0
	v_mul_f32_e32 v81, 0x45800000, v80
	v_cndmask_b32_e32 v80, v80, v81, vcc
	v_mul_f32_e32 v80, v157, v80
; __device__ __forceinline__ unsigned cvt_pk_bf16(float lo, float hi) { unsigned r; asm volatile("v_cvt_pk_bf16_f32 %0, %1, %2" : "=v"(r) : "v"(lo), "v"(hi)); return r; }
;     __device__ __forceinline__ void operator()(const f32x4 (&acc)[2][2][4][2], const Unit& u, int wr, int wc, int fr, int fq) const {
;     ...
;             for (int m = 0; m < 4; ++m) { const int row = row0 + ai * HALF + m * 16; const float rs = rsqrtf(rsv[ai][m] * (1.0f / 1024.0f) + 1e-6f) * sc;
; #pragma unroll
;                 for (int bj = 0; bj < 2; ++bj) { const f32x4 v0 = acc[ai][bj][m][0] * rs, v1 = acc[ai][bj][m][1] * rs;
;                     u32x4 w; w.x = cvt_pk_bf16(v0[0], v0[1]); w.y = cvt_pk_bf16(v0[2], v0[3]); w.z = cvt_pk_bf16(v1[0], v1[1]); w.w = cvt_pk_bf16(v1[2], v1[3]);
;                     *(u32x4*)(O + PB(col0 + bj * HALF) + (size_t)row * 64) = w; } }
; template <class Epi, class Sched, bool ALIGN_EPI = false, bool SP2 = false>
; __device__ __forceinline__ void gemm_phase(PG8_LAS unsigned char* lds, const Gemm g, const Sched& S, const Epi& E) {
;     ...
;         if (!has_next) break;
	v_pk_mul_f32 v[76:77], v[76:77], v[80:81] op_sel_hi:[1,0]
	v_pk_mul_f32 v[78:79], v[78:79], v[80:81] op_sel_hi:[1,0]
	v_pk_mul_f32 v[84:85], v[74:75], v[80:81] op_sel_hi:[1,0]
	v_pk_mul_f32 v[74:75], v[72:73], v[80:81] op_sel_hi:[1,0]
	v_cvt_pk_bf16_f32 v72, v76, v77
	v_cvt_pk_bf16_f32 v73, v78, v79
	v_lshl_add_u64 v[76:77], v[120:121], 0, v[82:83]
	v_pk_mul_f32 v[68:69], v[68:69], v[80:81] op_sel_hi:[1,0]
	v_cvt_pk_bf16_f32 v74, v74, v75
	v_cvt_pk_bf16_f32 v75, v84, v85
	global_store_dwordx4 v[76:77], v[72:75], off sc1
	v_pk_mul_f32 v[70:71], v[70:71], v[80:81] op_sel_hi:[1,0]
	s_nop 0
	v_pk_mul_f32 v[72:73], v[66:67], v[80:81] op_sel_hi:[1,0]
	v_pk_mul_f32 v[66:67], v[64:65], v[80:81] op_sel_hi:[1,0]
	v_cvt_pk_bf16_f32 v64, v68, v69
	v_lshl_add_u64 v[68:69], v[112:113], 0, v[82:83]
	v_cvt_pk_bf16_f32 v65, v70, v71
	v_cvt_pk_bf16_f32 v66, v66, v67
	v_cvt_pk_bf16_f32 v67, v72, v73
	global_store_dwordx4 v[68:69], v[64:67], off sc1
	s_nop 1
	v_fmamk_f32 v64, v245, 0x3a800000, v230
	v_cmp_gt_f32_e32 vcc, s37, v64
	v_mul_f32_e32 v65, 0x4b800000, v64
	s_nop 0
	v_cndmask_b32_e32 v64, v64, v65, vcc
	v_rsq_f32_e32 v64, v64
	s_nop 0
	v_mul_f32_e32 v65, 0x45800000, v64
	v_cndmask_b32_e32 v64, v64, v65, vcc
	v_mul_f32_e32 v64, v157, v64
	v_pk_mul_f32 v[60:61], v[60:61], v[64:65] op_sel_hi:[1,0]
	v_pk_mul_f32 v[62:63], v[62:63], v[64:65] op_sel_hi:[1,0]
	v_pk_mul_f32 v[66:67], v[58:59], v[64:65] op_sel_hi:[1,0]
	v_pk_mul_f32 v[58:59], v[56:57], v[64:65] op_sel_hi:[1,0]
	v_cvt_pk_bf16_f32 v56, v60, v61
	v_cvt_pk_bf16_f32 v57, v62, v63
	v_lshl_add_u64 v[60:61], v[120:121], 0, v[146:147]
	v_pk_mul_f32 v[52:53], v[52:53], v[64:65] op_sel_hi:[1,0]
	v_cvt_pk_bf16_f32 v58, v58, v59
	v_cvt_pk_bf16_f32 v59, v66, v67
	global_store_dwordx4 v[60:61], v[56:59], off sc1
	v_pk_mul_f32 v[54:55], v[54:55], v[64:65] op_sel_hi:[1,0]
	s_nop 0
	v_pk_mul_f32 v[56:57], v[50:51], v[64:65] op_sel_hi:[1,0]
	v_pk_mul_f32 v[50:51], v[48:49], v[64:65] op_sel_hi:[1,0]
	v_cvt_pk_bf16_f32 v48, v52, v53
	v_lshl_add_u64 v[52:53], v[112:113], 0, v[146:147]
	v_cvt_pk_bf16_f32 v49, v54, v55
	v_cvt_pk_bf16_f32 v50, v50, v51
	v_cvt_pk_bf16_f32 v51, v56, v57
	global_store_dwordx4 v[52:53], v[48:51], off sc1
	s_nop 1
	v_fmamk_f32 v48, v246, 0x3a800000, v230
	v_cmp_gt_f32_e32 vcc, s37, v48
	v_mul_f32_e32 v49, 0x4b800000, v48
	s_nop 0
	v_cndmask_b32_e32 v48, v48, v49, vcc
	v_rsq_f32_e32 v48, v48
	s_nop 0
	v_mul_f32_e32 v49, 0x45800000, v48
	v_cndmask_b32_e32 v48, v48, v49, vcc
	v_mul_f32_e32 v48, v157, v48
	v_pk_mul_f32 v[44:45], v[44:45], v[48:49] op_sel_hi:[1,0]
	v_pk_mul_f32 v[46:47], v[46:47], v[48:49] op_sel_hi:[1,0]
	v_pk_mul_f32 v[50:51], v[42:43], v[48:49] op_sel_hi:[1,0]
	v_pk_mul_f32 v[42:43], v[40:41], v[48:49] op_sel_hi:[1,0]
	v_cvt_pk_bf16_f32 v40, v44, v45
	v_cvt_pk_bf16_f32 v41, v46, v47
	v_lshl_add_u64 v[44:45], v[120:121], 0, v[144:145]
	v_pk_mul_f32 v[36:37], v[36:37], v[48:49] op_sel_hi:[1,0]
	v_cvt_pk_bf16_f32 v42, v42, v43
	v_cvt_pk_bf16_f32 v43, v50, v51
	global_store_dwordx4 v[44:45], v[40:43], off sc1
	v_pk_mul_f32 v[38:39], v[38:39], v[48:49] op_sel_hi:[1,0]
	s_nop 0
	v_pk_mul_f32 v[40:41], v[34:35], v[48:49] op_sel_hi:[1,0]
	v_pk_mul_f32 v[34:35], v[32:33], v[48:49] op_sel_hi:[1,0]
	v_cvt_pk_bf16_f32 v32, v36, v37
	v_lshl_add_u64 v[36:37], v[112:113], 0, v[144:145]
	v_cvt_pk_bf16_f32 v33, v38, v39
	v_cvt_pk_bf16_f32 v34, v34, v35
	v_cvt_pk_bf16_f32 v35, v40, v41
	global_store_dwordx4 v[36:37], v[32:35], off sc1
	s_nop 1
	v_fmamk_f32 v32, v247, 0x3a800000, v230
	v_cmp_gt_f32_e32 vcc, s37, v32
	v_mul_f32_e32 v33, 0x4b800000, v32
	s_nop 0
	v_cndmask_b32_e32 v32, v32, v33, vcc
	v_rsq_f32_e32 v32, v32
	s_nop 0
	v_mul_f32_e32 v33, 0x45800000, v32
	v_cndmask_b32_e32 v32, v32, v33, vcc
	v_mul_f32_e32 v32, v157, v32
	v_pk_mul_f32 v[28:29], v[28:29], v[32:33] op_sel_hi:[1,0]
	v_pk_mul_f32 v[30:31], v[30:31], v[32:33] op_sel_hi:[1,0]
	v_pk_mul_f32 v[34:35], v[26:27], v[32:33] op_sel_hi:[1,0]
	v_pk_mul_f32 v[26:27], v[24:25], v[32:33] op_sel_hi:[1,0]
	v_cvt_pk_bf16_f32 v24, v28, v29
	v_cvt_pk_bf16_f32 v25, v30, v31
	v_lshl_add_u64 v[28:29], v[120:121], 0, v[142:143]
	v_pk_mul_f32 v[20:21], v[20:21], v[32:33] op_sel_hi:[1,0]
	v_cvt_pk_bf16_f32 v26, v26, v27
	v_cvt_pk_bf16_f32 v27, v34, v35
	global_store_dwordx4 v[28:29], v[24:27], off sc1
	v_pk_mul_f32 v[22:23], v[22:23], v[32:33] op_sel_hi:[1,0]
	s_nop 0
	v_pk_mul_f32 v[24:25], v[18:19], v[32:33] op_sel_hi:[1,0]
	v_pk_mul_f32 v[18:19], v[16:17], v[32:33] op_sel_hi:[1,0]
	v_cvt_pk_bf16_f32 v16, v20, v21
	v_lshl_add_u64 v[20:21], v[112:113], 0, v[142:143]
	v_cvt_pk_bf16_f32 v17, v22, v23
	v_cvt_pk_bf16_f32 v18, v18, v19
	v_cvt_pk_bf16_f32 v19, v24, v25
	global_store_dwordx4 v[20:21], v[16:19], off sc1
	s_nop 1
	v_fmamk_f32 v16, v248, 0x3a800000, v230
	v_cmp_gt_f32_e32 vcc, s37, v16
	v_mul_f32_e32 v17, 0x4b800000, v16
	s_nop 0
	v_cndmask_b32_e32 v16, v16, v17, vcc
	v_rsq_f32_e32 v16, v16
	s_nop 0
	v_mul_f32_e32 v17, 0x45800000, v16
	v_cndmask_b32_e32 v16, v16, v17, vcc
	v_mul_f32_e32 v16, v157, v16
	v_pk_mul_f32 v[12:13], v[12:13], v[16:17] op_sel_hi:[1,0]
	v_pk_mul_f32 v[14:15], v[14:15], v[16:17] op_sel_hi:[1,0]
	v_pk_mul_f32 v[18:19], v[10:11], v[16:17] op_sel_hi:[1,0]
	v_pk_mul_f32 v[10:11], v[8:9], v[16:17] op_sel_hi:[1,0]
	v_cvt_pk_bf16_f32 v8, v12, v13
	v_cvt_pk_bf16_f32 v9, v14, v15
	v_lshl_add_u64 v[12:13], v[120:121], 0, v[140:141]
	v_pk_mul_f32 v[4:5], v[4:5], v[16:17] op_sel_hi:[1,0]
	v_cvt_pk_bf16_f32 v10, v10, v11
	v_cvt_pk_bf16_f32 v11, v18, v19
	global_store_dwordx4 v[12:13], v[8:11], off sc1
	s_andn2_b64 vcc, exec, s[4:5]
	v_pk_mul_f32 v[6:7], v[6:7], v[16:17] op_sel_hi:[1,0]
	v_pk_mul_f32 v[8:9], v[2:3], v[16:17] op_sel_hi:[1,0]
	v_pk_mul_f32 v[2:3], v[0:1], v[16:17] op_sel_hi:[1,0]
	v_cvt_pk_bf16_f32 v0, v4, v5
	v_lshl_add_u64 v[4:5], v[112:113], 0, v[140:141]
	v_cvt_pk_bf16_f32 v1, v6, v7
	v_cvt_pk_bf16_f32 v2, v2, v3
	v_cvt_pk_bf16_f32 v3, v8, v9
	global_store_dwordx4 v[4:5], v[0:3], off sc1
	s_cbranch_vccnz .LBB0_131
	s_andn2_b64 vcc, exec, s[8:9]
	s_cbranch_vccnz .LBB0_130
	s_barrier
	s_branch .LBB0_130
